# attention item tail: the four Z stores staged through a wave-private LDS image so each store writes full 128 B row segments (was 16 B per lane into 64 rows)
# baseline (speedup 1.0000x reference)
.LBB0_456:
	s_or_b64 exec, exec, s[82:83]
	v_readlane_b32 s0, v245, 48
	v_lshlrev_b32_e32 v34, 6, v184
	v_readlane_b32 s1, v245, 49
	v_lshlrev_b32_e32 v46, 1, v34
	v_mov_b32_e32 v47, v133
	v_lshl_add_u64 v[36:37], s[0:1], 0, v[150:151]
	v_lshl_add_u64 v[34:35], v[36:37], 0, v[46:47]
	v_mov_b32_e32 v145, v133
	v_lshl_add_u64 v[48:49], v[34:35], 0, v[144:145]
	s_waitcnt vmcnt(4)
	v_mov_b32_e32 v34, v226
	v_mov_b32_e32 v35, v227
	v_mov_b32_e32 v36, v228
	v_mov_b32_e32 v37, v229
	v_mov_b32_e32 v38, v230
	v_mov_b32_e32 v39, v231
	v_mov_b32_e32 v40, v232
	v_mov_b32_e32 v41, v233
	v_mov_b32_e32 v42, v234
	v_mov_b32_e32 v43, v235
	v_mov_b32_e32 v44, v236
	v_mov_b32_e32 v45, v237
	v_lshlrev_b64 v[50:51], 11, v[146:147]
	v_lshl_add_u64 v[50:51], s[96:97], 0, v[50:51]
	v_lshl_add_u64 v[50:51], v[50:51], 0, v[46:47]
	v_mov_b32_e32 v46, v238
	v_mov_b32_e32 v47, v239
	v_mov_b32_e32 v48, v240
	v_mov_b32_e32 v49, v241
	ds_bpermute_b32 v54, v172, v149
	v_permlane32_swap_b32_e32 v2, v18
	v_permlane32_swap_b32_e32 v3, v19
	s_waitcnt lgkmcnt(0)
	v_add_f32_e32 v54, v149, v54
	v_rcp_f32_e32 v54, v54
	v_permlane32_swap_b32_e32 v4, v20
	v_permlane32_swap_b32_e32 v5, v21
	v_permlane32_swap_b32_e32 v6, v22
	v_permlane32_swap_b32_e32 v7, v23
	v_permlane32_swap_b32_e32 v8, v24
	v_permlane32_swap_b32_e32 v9, v25
	s_mov_b64 s[0:1], 0x13a0400
	s_mov_b32 s3, 0x13a0000
	v_lshl_add_u64 v[50:51], v[50:51], 0, v[144:145]
	v_pk_mul_f32 v[2:3], v[54:55], v[2:3] op_sel_hi:[0,1]
	v_pk_mul_f32 v[18:19], v[54:55], v[18:19] op_sel_hi:[0,1]
	v_pk_mul_f32 v[4:5], v[54:55], v[4:5] op_sel_hi:[0,1]
	v_pk_mul_f32 v[20:21], v[54:55], v[20:21] op_sel_hi:[0,1]
	v_pk_mul_f32 v[22:23], v[54:55], v[22:23] op_sel_hi:[0,1]
	v_pk_mul_f32 v[24:25], v[54:55], v[24:25] op_sel_hi:[0,1]
	v_lshl_add_u64 v[52:53], v[50:51], 0, s[0:1]
	v_add_co_u32_e32 v50, vcc, s3, v50
	v_pk_mul_f32 v[6:7], v[54:55], v[6:7] op_sel_hi:[0,1]
	v_pk_mul_f32 v[8:9], v[54:55], v[8:9] op_sel_hi:[0,1]
	v_permlane32_swap_b32_e32 v10, v26
	v_addc_co_u32_e32 v51, vcc, 0, v51, vcc
	v_permlane32_swap_b32_e32 v11, v27
	v_permlane32_swap_b32_e32 v12, v28
	v_permlane32_swap_b32_e32 v13, v29
	v_permlane32_swap_b32_e32 v14, v30
	v_permlane32_swap_b32_e32 v15, v31
	v_permlane32_swap_b32_e32 v16, v32
	v_permlane32_swap_b32_e32 v17, v33
	v_add_u32_e32 v161, s78, v161
	s_movk_i32 s0, 0x5ff
	v_cmp_lt_i32_e32 vcc, s0, v161
	s_or_b64 s[84:85], vcc, s[84:85]
	v_lshlrev_b32_e32 v56, 16, v34
	v_and_b32_e32 v57, 0xffff0000, v34
	v_lshlrev_b32_e32 v34, 16, v35
	v_and_b32_e32 v35, 0xffff0000, v35
	v_lshlrev_b32_e32 v58, 16, v36
	v_and_b32_e32 v59, 0xffff0000, v36
	v_lshlrev_b32_e32 v36, 16, v37
	v_and_b32_e32 v37, 0xffff0000, v37
	v_lshlrev_b32_e32 v62, 16, v40
	v_and_b32_e32 v63, 0xffff0000, v40
	v_lshlrev_b32_e32 v40, 16, v41
	v_and_b32_e32 v41, 0xffff0000, v41
	v_lshlrev_b32_e32 v60, 16, v38
	v_and_b32_e32 v61, 0xffff0000, v38
	v_lshlrev_b32_e32 v38, 16, v39
	v_and_b32_e32 v39, 0xffff0000, v39
	v_pk_mul_f32 v[2:3], v[2:3], v[56:57]
	v_pk_mul_f32 v[18:19], v[18:19], v[58:59]
	v_pk_mul_f32 v[34:35], v[4:5], v[34:35]
	v_pk_mul_f32 v[20:21], v[20:21], v[36:37]
	v_pk_mul_f32 v[22:23], v[22:23], v[62:63]
	v_pk_mul_f32 v[24:25], v[24:25], v[40:41]
	v_pk_mul_f32 v[6:7], v[6:7], v[60:61]
	v_pk_mul_f32 v[36:37], v[8:9], v[38:39]
	v_cvt_pk_bf16_f32 v2, v2, v3
	v_cvt_pk_bf16_f32 v4, v18, v19
	v_cvt_pk_bf16_f32 v3, v34, v35
	v_cvt_pk_bf16_f32 v5, v20, v21
	v_cvt_pk_bf16_f32 v8, v22, v23
	v_cvt_pk_bf16_f32 v9, v24, v25
	v_lshlrev_b32_e32 v64, 16, v42
	v_and_b32_e32 v65, 0xffff0000, v42
	v_lshlrev_b32_e32 v42, 16, v43
	v_and_b32_e32 v43, 0xffff0000, v43
	v_cvt_pk_bf16_f32 v6, v6, v7
	v_cvt_pk_bf16_f32 v7, v36, v37
	v_and_b32_e32 v68, 31, v212
	v_mul_u32_u24_e32 v68, 0x90, v68
	v_bfe_u32 v69, v212, 5, 1
	v_lshl_add_u32 v68, v69, 6, v68
	v_bfe_u32 v69, v212, 6, 2
	v_mul_u32_u24_e32 v69, 0x1200, v69
	v_add3_u32 v68, v68, v69, v160
	v_add_u32_e32 v68, 0xa000, v68
	ds_write_b128 v68, v[2:5]
	ds_write_b128 v68, v[6:9] offset:16
	v_lshlrev_b32_e32 v66, 16, v44
	v_pk_mul_f32 v[2:3], v[54:55], v[10:11] op_sel_hi:[0,1]
	v_pk_mul_f32 v[8:9], v[54:55], v[12:13] op_sel_hi:[0,1]
	v_pk_mul_f32 v[2:3], v[2:3], v[64:65]
	v_pk_mul_f32 v[8:9], v[8:9], v[42:43]
	v_and_b32_e32 v67, 0xffff0000, v44
	v_cvt_pk_bf16_f32 v2, v2, v3
	v_pk_mul_f32 v[4:5], v[54:55], v[26:27] op_sel_hi:[0,1]
	v_lshlrev_b32_e32 v6, 16, v45
	v_and_b32_e32 v7, 0xffff0000, v45
	v_cvt_pk_bf16_f32 v3, v8, v9
	v_pk_mul_f32 v[8:9], v[54:55], v[28:29] op_sel_hi:[0,1]
	v_pk_mul_f32 v[4:5], v[4:5], v[66:67]
	v_pk_mul_f32 v[6:7], v[8:9], v[6:7]
	v_cvt_pk_bf16_f32 v4, v4, v5
	v_cvt_pk_bf16_f32 v5, v6, v7
	ds_write_b128 v68, v[2:5] offset:32
	v_pk_mul_f32 v[6:7], v[54:55], v[16:17] op_sel_hi:[0,1]
	v_pk_mul_f32 v[8:9], v[54:55], v[32:33] op_sel_hi:[0,1]
	v_lshlrev_b32_e32 v2, 16, v46
	v_and_b32_e32 v3, 0xffff0000, v46
	v_pk_mul_f32 v[4:5], v[54:55], v[14:15] op_sel_hi:[0,1]
	v_pk_mul_f32 v[2:3], v[4:5], v[2:3]
	v_lshlrev_b32_e32 v4, 16, v47
	v_and_b32_e32 v5, 0xffff0000, v47
	v_pk_mul_f32 v[4:5], v[6:7], v[4:5]
	v_cvt_pk_bf16_f32 v2, v2, v3
	v_cvt_pk_bf16_f32 v3, v4, v5
	v_lshlrev_b32_e32 v4, 16, v48
	v_and_b32_e32 v5, 0xffff0000, v48
	v_pk_mul_f32 v[6:7], v[54:55], v[30:31] op_sel_hi:[0,1]
	v_pk_mul_f32 v[4:5], v[6:7], v[4:5]
	v_lshlrev_b32_e32 v6, 16, v49
	v_and_b32_e32 v7, 0xffff0000, v49
	v_pk_mul_f32 v[6:7], v[8:9], v[6:7]
	v_cvt_pk_bf16_f32 v4, v4, v5
	v_cvt_pk_bf16_f32 v5, v6, v7
	ds_write_b128 v68, v[2:5] offset:48
	v_and_b32_e32 v70, 63, v212
	v_lshrrev_b32_e32 v71, 3, v70
	v_and_b32_e32 v72, 7, v70
	v_mul_u32_u24_e32 v73, 0x240, v71
	v_lshl_add_u32 v73, v72, 4, v73
	v_add3_u32 v74, v73, v69, v160
	v_add_u32_e32 v74, 0xa000, v74
	ds_read_b128 v[76:79], v74
	ds_read_b128 v[80:83], v74 offset:144
	ds_read_b128 v[84:87], v74 offset:288
	ds_read_b128 v[88:91], v74 offset:432
	v_and_b32_e32 v75, 31, v212
	v_lshlrev_b32_e32 v71, 2, v71
	v_sub_u32_e32 v71, v71, v75
	v_lshlrev_b32_e32 v72, 4, v72
	v_bfe_u32 v75, v212, 5, 1
	v_lshlrev_b32_e32 v75, 6, v75
	v_sub_u32_e32 v72, v72, v75
	v_lshl_add_u32 v70, v71, 11, v72
	v_ashrrev_i32_e32 v71, 31, v70
	v_lshl_add_u64 v[72:73], v[52:53], 0, v[70:71]
	s_mov_b64 s[98:99], 0x1000
	v_lshl_add_u64 v[92:93], v[72:73], 0, s[98:99]
	s_waitcnt lgkmcnt(3)
	global_store_dwordx4 v[72:73], v[76:79], off
	s_waitcnt lgkmcnt(2)
	global_store_dwordx4 v[72:73], v[80:83], off offset:2048
	s_waitcnt lgkmcnt(1)
	global_store_dwordx4 v[92:93], v[84:87], off
	s_waitcnt lgkmcnt(0)
	global_store_dwordx4 v[92:93], v[88:91], off offset:2048
	s_andn2_b64 exec, exec, s[84:85]
	s_cbranch_execz .LBB0_551
